# combo+gblk + EpiPool: pool_scale vectors loaded once into dead fragment regs, per-store reload and vmcnt(1)/(0) waits removed
# speedup vs baseline: 1.0146x; 1.0003x over previous
; __device__ __forceinline__ u32x4 pack8(f32x4 a, f32x4 b) { u32x4 w; w.x = cvt_pk_bf16(a[0], a[1]); w.y = cvt_pk_bf16(a[2], a[3]); w.z = cvt_pk_bf16(b[0], b[1]); w.w = cvt_pk_bf16(b[2], b[3]); return w; }
; __device__ __forceinline__ void unpack8(u32x4 g, f32x4& a, f32x4& b) { a = (f32x4){bf_lo(g.x), bf_hi(g.x), bf_lo(g.y), bf_hi(g.y)}; b = (f32x4){bf_lo(g.z), bf_hi(g.z), bf_lo(g.w), bf_hi(g.w)}; }
; #define EPI_OPAQUE asm volatile("" : "+v"(fr), "+v"(fq));
;     __device__ __forceinline__ void operator()(f32x4 (&acc)[2][2][4][2], const Unit& u, int wr, int wc, int fr, int fq) const {
;         EPI_OPAQUE
; #pragma unroll
;         for (int ai = 0; ai < 2; ++ai) {
;             u32x4 zz[4][2];
; #pragma unroll
;             for (int m = 0; m < 4; ++m)
; #pragma unroll
;                 for (int bj = 0; bj < 2; ++bj) { const int row = u.pm * 256 + ai * 128 + wr * 64 + m * 16 + fr, col = u.pn * 256 + bj * 128 + wc * 32 + 8 * fq;
;                     zz[m][bj] = *(const u32x4*)(P + (size_t)row * NCO + OBZ + col); }
;             asm volatile("" ::: "memory");
; #pragma unroll
;             for (int m = 0; m < 4; ++m)
; #pragma unroll
;                 for (int bj = 0; bj < 2; ++bj) { const int row = u.pm * 256 + ai * 128 + wr * 64 + m * 16 + fr, col = u.pn * 256 + bj * 128 + wc * 32 + 8 * fq;
;                     const f32x4 s0 = *(const f32x4*)(pscale + col), s1 = *(const f32x4*)(pscale + col + 4);
;                     f32x4 z0, z1; unpack8(zz[m][bj], z0, z1);
;                     *(u32x4*)(Y + (size_t)row * YW + EW + col) = pack8(acc[ai][bj][m][0] * s0 * z0, acc[ai][bj][m][1] * s1 * z1); }
;             asm volatile("" ::: "memory");
;         }
;     }
.LBB0_492:
	s_lshl_b32 s4, s92, 8
	v_mov_b32_e32 v118, v180
	v_mov_b32_e32 v119, v1
	s_add_i32 s4, s4, s22
	v_mov_b64_e32 v[178:179], s[68:69]
	v_add_u32_e32 v183, s4, v119
	s_lshl_b32 s4, s82, 8
	s_or_b32 s4, s4, s23
	v_lshl_add_u32 v172, v118, 3, s4
	v_ashrrev_i32_e32 v173, 31, v172
	v_mad_i64_i32 v[118:119], s[4:5], v183, s33, v[178:179]
	v_lshl_add_u64 v[118:119], v[118:119], 0, s[38:39]
	v_lshlrev_b64 v[174:175], 1, v[172:173]
	v_lshl_add_u64 v[120:121], v[118:119], 0, v[174:175]
	global_load_dwordx4 v[208:211], v[120:121], off
	v_add_u32_e32 v120, 0x80, v172
	v_ashrrev_i32_e32 v121, 31, v120
	v_lshlrev_b64 v[176:177], 1, v[120:121]
	v_lshl_add_u64 v[118:119], v[118:119], 0, v[176:177]
	v_add_u32_e32 v222, 16, v183
	global_load_dwordx4 v[154:157], v[118:119], off
	v_mad_i64_i32 v[118:119], s[4:5], v222, s33, v[178:179]
	v_lshl_add_u64 v[118:119], v[118:119], 0, s[38:39]
	v_lshl_add_u64 v[120:121], v[118:119], 0, v[174:175]
	v_lshl_add_u64 v[118:119], v[118:119], 0, v[176:177]
	v_add_u32_e32 v185, 32, v183
	global_load_dwordx4 v[150:153], v[120:121], off
	global_load_dwordx4 v[146:149], v[118:119], off
	v_mad_i64_i32 v[118:119], s[4:5], v185, s33, v[178:179]
	v_lshl_add_u64 v[118:119], v[118:119], 0, s[38:39]
	v_lshl_add_u64 v[120:121], v[118:119], 0, v[174:175]
	v_lshl_add_u64 v[118:119], v[118:119], 0, v[176:177]
	v_add_u32_e32 v184, 48, v183
	global_load_dwordx4 v[142:145], v[120:121], off
	global_load_dwordx4 v[138:141], v[118:119], off
	v_mad_i64_i32 v[118:119], s[4:5], v184, s33, v[178:179]
	v_lshl_add_u64 v[118:119], v[118:119], 0, s[38:39]
	v_lshl_add_u64 v[120:121], v[118:119], 0, v[174:175]
	v_lshl_add_u64 v[118:119], v[118:119], 0, v[176:177]
	global_load_dwordx4 v[126:129], v[120:121], off
	v_lshl_add_u64 v[172:173], v[172:173], 2, s[44:45]
	global_load_dwordx4 v[118:121], v[118:119], off
	global_load_dwordx4 v[228:231], v[172:173], off offset:16
	global_load_dwordx4 v[224:227], v[172:173], off
	global_load_dwordx4 v[236:239], v[172:173], off offset:528
	global_load_dwordx4 v[232:235], v[172:173], off offset:512
	s_andn2_b64 vcc, exec, s[52:53]
	s_waitcnt vmcnt(0)
	v_lshlrev_b32_e32 v186, 16, v208
	v_and_b32_e32 v187, 0xffff0000, v208
	v_lshlrev_b32_e32 v220, 16, v210
	v_and_b32_e32 v221, 0xffff0000, v210
	v_lshlrev_b32_e32 v208, 16, v209
	v_and_b32_e32 v209, 0xffff0000, v209
	v_lshlrev_b32_e32 v210, 16, v211
	v_and_b32_e32 v211, 0xffff0000, v211
	v_pk_mul_f32 v[130:131], v[130:131], v[228:229]
	v_pk_mul_f32 v[134:135], v[134:135], v[224:225]
	v_pk_mul_f32 v[136:137], v[136:137], v[226:227]
	v_pk_mul_f32 v[134:135], v[134:135], v[186:187]
	v_pk_mul_f32 v[132:133], v[132:133], v[230:231]
	v_pk_mul_f32 v[130:131], v[130:131], v[220:221]
	v_pk_mul_f32 v[136:137], v[136:137], v[208:209]
	v_pk_mul_f32 v[186:187], v[132:133], v[210:211]
	v_cvt_pk_bf16_f32 v132, v134, v135
	v_cvt_pk_bf16_f32 v134, v130, v131
	v_mov_b64_e32 v[130:131], s[70:71]
	v_cvt_pk_bf16_f32 v133, v136, v137
	v_mad_i64_i32 v[136:137], s[4:5], v183, s13, v[130:131]
	v_cvt_pk_bf16_f32 v135, v186, v187
	v_lshl_add_u64 v[136:137], v[136:137], 0, v[174:175]
	global_store_dwordx4 v[136:137], v[132:135], off offset:2048
	s_nop 1
	s_nop 0
	v_lshlrev_b32_e32 v186, 16, v154
	v_and_b32_e32 v187, 0xffff0000, v154
	v_lshlrev_b32_e32 v154, 16, v155
	v_and_b32_e32 v155, 0xffff0000, v155
	v_lshlrev_b32_e32 v212, 16, v156
	v_and_b32_e32 v213, 0xffff0000, v156
	v_lshlrev_b32_e32 v156, 16, v157
	v_and_b32_e32 v157, 0xffff0000, v157
	v_pk_mul_f32 v[116:117], v[116:117], v[238:239]
	v_pk_mul_f32 v[124:125], v[124:125], v[234:235]
	v_pk_mul_f32 v[122:123], v[122:123], v[232:233]
	v_pk_mul_f32 v[114:115], v[114:115], v[236:237]
	v_pk_mul_f32 v[124:125], v[124:125], v[154:155]
	v_pk_mul_f32 v[122:123], v[122:123], v[186:187]
	v_pk_mul_f32 v[132:133], v[116:117], v[156:157]
	v_pk_mul_f32 v[116:117], v[114:115], v[212:213]
	v_cvt_pk_bf16_f32 v114, v122, v123
	v_cvt_pk_bf16_f32 v115, v124, v125
	v_cvt_pk_bf16_f32 v116, v116, v117
	v_cvt_pk_bf16_f32 v117, v132, v133
	global_store_dwordx4 v[136:137], v[114:117], off offset:2304
	s_nop 1
	s_nop 0
	v_lshlrev_b32_e32 v132, 16, v150
	v_and_b32_e32 v133, 0xffff0000, v150
	v_lshlrev_b32_e32 v134, 16, v151
	v_and_b32_e32 v135, 0xffff0000, v151
	v_lshlrev_b32_e32 v136, 16, v152
	v_and_b32_e32 v137, 0xffff0000, v152
	v_lshlrev_b32_e32 v150, 16, v153
	v_and_b32_e32 v151, 0xffff0000, v153
	v_pk_mul_f32 v[108:109], v[108:109], v[230:231]
	v_pk_mul_f32 v[110:111], v[110:111], v[224:225]
	v_pk_mul_f32 v[112:113], v[112:113], v[226:227]
	v_pk_mul_f32 v[110:111], v[110:111], v[132:133]
	v_pk_mul_f32 v[106:107], v[106:107], v[228:229]
	v_pk_mul_f32 v[112:113], v[112:113], v[134:135]
	v_pk_mul_f32 v[114:115], v[108:109], v[150:151]
	v_pk_mul_f32 v[108:109], v[106:107], v[136:137]
	v_cvt_pk_bf16_f32 v106, v110, v111
	v_mad_i64_i32 v[110:111], s[4:5], v222, s13, v[130:131]
	v_cvt_pk_bf16_f32 v107, v112, v113
	v_cvt_pk_bf16_f32 v108, v108, v109
	v_cvt_pk_bf16_f32 v109, v114, v115
	v_lshl_add_u64 v[114:115], v[110:111], 0, v[174:175]
	global_store_dwordx4 v[114:115], v[106:109], off offset:2048
	s_nop 1
	s_nop 0
	v_lshlrev_b32_e32 v116, 16, v146
	v_and_b32_e32 v117, 0xffff0000, v146
	v_lshlrev_b32_e32 v122, 16, v147
	v_and_b32_e32 v123, 0xffff0000, v147
	v_lshlrev_b32_e32 v124, 16, v148
	v_and_b32_e32 v125, 0xffff0000, v148
	v_lshlrev_b32_e32 v132, 16, v149
	v_and_b32_e32 v133, 0xffff0000, v149
	v_pk_mul_f32 v[100:101], v[100:101], v[238:239]
	v_pk_mul_f32 v[104:105], v[104:105], v[234:235]
	v_pk_mul_f32 v[102:103], v[102:103], v[232:233]
	v_pk_mul_f32 v[98:99], v[98:99], v[236:237]
	v_pk_mul_f32 v[104:105], v[104:105], v[122:123]
; __device__ __forceinline__ u32x4 pack8(f32x4 a, f32x4 b) { u32x4 w; w.x = cvt_pk_bf16(a[0], a[1]); w.y = cvt_pk_bf16(a[2], a[3]); w.z = cvt_pk_bf16(b[0], b[1]); w.w = cvt_pk_bf16(b[2], b[3]); return w; }
; __device__ __forceinline__ void unpack8(u32x4 g, f32x4& a, f32x4& b) { a = (f32x4){bf_lo(g.x), bf_hi(g.x), bf_lo(g.y), bf_hi(g.y)}; b = (f32x4){bf_lo(g.z), bf_hi(g.z), bf_lo(g.w), bf_hi(g.w)}; }
; #define EPI_OPAQUE asm volatile("" : "+v"(fr), "+v"(fq));
;     __device__ __forceinline__ void operator()(f32x4 (&acc)[2][2][4][2], const Unit& u, int wr, int wc, int fr, int fq) const {
;         EPI_OPAQUE
; #pragma unroll
;         for (int ai = 0; ai < 2; ++ai) {
;             u32x4 zz[4][2];
; #pragma unroll
;             for (int m = 0; m < 4; ++m)
; #pragma unroll
;                 for (int bj = 0; bj < 2; ++bj) { const int row = u.pm * 256 + ai * 128 + wr * 64 + m * 16 + fr, col = u.pn * 256 + bj * 128 + wc * 32 + 8 * fq;
;                     zz[m][bj] = *(const u32x4*)(P + (size_t)row * NCO + OBZ + col); }
;             asm volatile("" ::: "memory");
; #pragma unroll
;             for (int m = 0; m < 4; ++m)
; #pragma unroll
;                 for (int bj = 0; bj < 2; ++bj) { const int row = u.pm * 256 + ai * 128 + wr * 64 + m * 16 + fr, col = u.pn * 256 + bj * 128 + wc * 32 + 8 * fq;
;                     const f32x4 s0 = *(const f32x4*)(pscale + col), s1 = *(const f32x4*)(pscale + col + 4);
;                     f32x4 z0, z1; unpack8(zz[m][bj], z0, z1);
;                     *(u32x4*)(Y + (size_t)row * YW + EW + col) = pack8(acc[ai][bj][m][0] * s0 * z0, acc[ai][bj][m][1] * s1 * z1); }
;             asm volatile("" ::: "memory");
;         }
;     }
	v_pk_mul_f32 v[102:103], v[102:103], v[116:117]
	v_pk_mul_f32 v[106:107], v[100:101], v[132:133]
	v_pk_mul_f32 v[100:101], v[98:99], v[124:125]
	v_cvt_pk_bf16_f32 v98, v102, v103
	v_cvt_pk_bf16_f32 v99, v104, v105
	v_cvt_pk_bf16_f32 v100, v100, v101
	v_cvt_pk_bf16_f32 v101, v106, v107
	global_store_dwordx4 v[114:115], v[98:101], off offset:2304
	s_nop 1
	s_nop 0
	v_lshlrev_b32_e32 v106, 16, v142
	v_and_b32_e32 v107, 0xffff0000, v142
	v_lshlrev_b32_e32 v108, 16, v143
	v_and_b32_e32 v109, 0xffff0000, v143
	v_lshlrev_b32_e32 v110, 16, v144
	v_and_b32_e32 v111, 0xffff0000, v144
	v_lshlrev_b32_e32 v112, 16, v145
	v_and_b32_e32 v113, 0xffff0000, v145
	v_pk_mul_f32 v[92:93], v[92:93], v[230:231]
	v_pk_mul_f32 v[94:95], v[94:95], v[224:225]
	v_pk_mul_f32 v[96:97], v[96:97], v[226:227]
	v_pk_mul_f32 v[94:95], v[94:95], v[106:107]
	v_pk_mul_f32 v[90:91], v[90:91], v[228:229]
	v_pk_mul_f32 v[96:97], v[96:97], v[108:109]
	v_pk_mul_f32 v[98:99], v[92:93], v[112:113]
	v_pk_mul_f32 v[92:93], v[90:91], v[110:111]
	v_cvt_pk_bf16_f32 v90, v94, v95
	v_mad_i64_i32 v[94:95], s[4:5], v185, s13, v[130:131]
	v_cvt_pk_bf16_f32 v91, v96, v97
	v_cvt_pk_bf16_f32 v92, v92, v93
	v_cvt_pk_bf16_f32 v93, v98, v99
	v_lshl_add_u64 v[98:99], v[94:95], 0, v[174:175]
	global_store_dwordx4 v[98:99], v[90:93], off offset:2048
	s_nop 1
	s_nop 0
	v_lshlrev_b32_e32 v100, 16, v138
	v_and_b32_e32 v101, 0xffff0000, v138
	v_lshlrev_b32_e32 v102, 16, v139
	v_and_b32_e32 v103, 0xffff0000, v139
	v_lshlrev_b32_e32 v104, 16, v140
	v_and_b32_e32 v105, 0xffff0000, v140
	v_lshlrev_b32_e32 v106, 16, v141
	v_and_b32_e32 v107, 0xffff0000, v141
	v_pk_mul_f32 v[84:85], v[84:85], v[238:239]
	v_pk_mul_f32 v[88:89], v[88:89], v[234:235]
	v_pk_mul_f32 v[86:87], v[86:87], v[232:233]
	v_pk_mul_f32 v[82:83], v[82:83], v[236:237]
	v_pk_mul_f32 v[88:89], v[88:89], v[102:103]
	v_pk_mul_f32 v[86:87], v[86:87], v[100:101]
	v_pk_mul_f32 v[90:91], v[84:85], v[106:107]
	v_pk_mul_f32 v[84:85], v[82:83], v[104:105]
	v_cvt_pk_bf16_f32 v82, v86, v87
	v_cvt_pk_bf16_f32 v83, v88, v89
	v_cvt_pk_bf16_f32 v84, v84, v85
	v_cvt_pk_bf16_f32 v85, v90, v91
	global_store_dwordx4 v[98:99], v[82:85], off offset:2304
	s_nop 1
	s_nop 0
	v_lshlrev_b32_e32 v90, 16, v126
	v_and_b32_e32 v91, 0xffff0000, v126
	v_lshlrev_b32_e32 v92, 16, v127
	v_and_b32_e32 v93, 0xffff0000, v127
	v_lshlrev_b32_e32 v94, 16, v128
	v_and_b32_e32 v95, 0xffff0000, v128
	v_lshlrev_b32_e32 v96, 16, v129
	v_and_b32_e32 v97, 0xffff0000, v129
	v_add_u32_e32 v101, 0x80, v183
	v_add_u32_e32 v100, 0x90, v183
	v_add_u32_e32 v99, 0xa0, v183
	v_add_u32_e32 v98, 0xb0, v183
	v_pk_mul_f32 v[76:77], v[76:77], v[230:231]
	v_pk_mul_f32 v[78:79], v[78:79], v[224:225]
	v_pk_mul_f32 v[80:81], v[80:81], v[226:227]
	v_pk_mul_f32 v[78:79], v[78:79], v[90:91]
	v_pk_mul_f32 v[74:75], v[74:75], v[228:229]
	v_pk_mul_f32 v[80:81], v[80:81], v[92:93]
	v_pk_mul_f32 v[82:83], v[76:77], v[96:97]
	v_pk_mul_f32 v[76:77], v[74:75], v[94:95]
	v_cvt_pk_bf16_f32 v74, v78, v79
	v_mad_i64_i32 v[78:79], s[4:5], v184, s13, v[130:131]
	v_cvt_pk_bf16_f32 v75, v80, v81
	v_cvt_pk_bf16_f32 v76, v76, v77
	v_cvt_pk_bf16_f32 v77, v82, v83
	v_lshl_add_u64 v[82:83], v[78:79], 0, v[174:175]
	global_store_dwordx4 v[82:83], v[74:77], off offset:2048
	s_nop 1
	s_nop 0
	v_lshlrev_b32_e32 v84, 16, v118
	v_and_b32_e32 v85, 0xffff0000, v118
	v_lshlrev_b32_e32 v86, 16, v119
	v_and_b32_e32 v87, 0xffff0000, v119
	v_lshlrev_b32_e32 v88, 16, v120
	v_and_b32_e32 v89, 0xffff0000, v120
	v_lshlrev_b32_e32 v90, 16, v121
	v_and_b32_e32 v91, 0xffff0000, v121
	v_pk_mul_f32 v[68:69], v[68:69], v[238:239]
	v_pk_mul_f32 v[72:73], v[72:73], v[234:235]
	v_pk_mul_f32 v[70:71], v[70:71], v[232:233]
	v_pk_mul_f32 v[66:67], v[66:67], v[236:237]
	v_pk_mul_f32 v[72:73], v[72:73], v[86:87]
	v_pk_mul_f32 v[70:71], v[70:71], v[84:85]
	v_pk_mul_f32 v[74:75], v[68:69], v[90:91]
	v_pk_mul_f32 v[68:69], v[66:67], v[88:89]
	v_cvt_pk_bf16_f32 v66, v70, v71
	v_cvt_pk_bf16_f32 v67, v72, v73
	v_cvt_pk_bf16_f32 v68, v68, v69
	v_cvt_pk_bf16_f32 v69, v74, v75
	global_store_dwordx4 v[82:83], v[66:69], off offset:2304
	s_nop 1
	s_nop 1
	v_mad_i64_i32 v[66:67], s[4:5], v101, s33, v[178:179]
	v_lshl_add_u64 v[66:67], v[66:67], 0, s[38:39]
	v_lshl_add_u64 v[68:69], v[66:67], 0, v[174:175]
	v_lshl_add_u64 v[66:67], v[66:67], 0, v[176:177]
	global_load_dwordx4 v[94:97], v[68:69], off
	global_load_dwordx4 v[90:93], v[66:67], off
	v_mad_i64_i32 v[66:67], s[4:5], v100, s33, v[178:179]
	v_lshl_add_u64 v[66:67], v[66:67], 0, s[38:39]
	v_lshl_add_u64 v[68:69], v[66:67], 0, v[174:175]
	v_lshl_add_u64 v[66:67], v[66:67], 0, v[176:177]
	global_load_dwordx4 v[86:89], v[68:69], off
	global_load_dwordx4 v[82:85], v[66:67], off
	v_mad_i64_i32 v[66:67], s[4:5], v99, s33, v[178:179]
	v_lshl_add_u64 v[66:67], v[66:67], 0, s[38:39]
	v_lshl_add_u64 v[68:69], v[66:67], 0, v[174:175]
	v_lshl_add_u64 v[66:67], v[66:67], 0, v[176:177]
	global_load_dwordx4 v[78:81], v[68:69], off
	global_load_dwordx4 v[70:73], v[66:67], off
	v_mad_i64_i32 v[66:67], s[4:5], v98, s33, v[178:179]
	v_lshl_add_u64 v[66:67], v[66:67], 0, s[38:39]
	v_lshl_add_u64 v[68:69], v[66:67], 0, v[174:175]
	v_lshl_add_u64 v[66:67], v[66:67], 0, v[176:177]
	global_load_dwordx4 v[74:77], v[68:69], off
	s_waitcnt vmcnt(6)
	v_lshlrev_b32_e32 v110, 16, v94
	global_load_dwordx4 v[66:69], v[66:67], off
	v_and_b32_e32 v111, 0xffff0000, v94
	v_lshlrev_b32_e32 v94, 16, v95
	v_and_b32_e32 v95, 0xffff0000, v95
	v_lshlrev_b32_e32 v112, 16, v96
	v_and_b32_e32 v113, 0xffff0000, v96
	v_lshlrev_b32_e32 v96, 16, v97
	v_and_b32_e32 v97, 0xffff0000, v97
	s_waitcnt vmcnt(0)
; __device__ __forceinline__ u32x4 pack8(f32x4 a, f32x4 b) { u32x4 w; w.x = cvt_pk_bf16(a[0], a[1]); w.y = cvt_pk_bf16(a[2], a[3]); w.z = cvt_pk_bf16(b[0], b[1]); w.w = cvt_pk_bf16(b[2], b[3]); return w; }
; __device__ __forceinline__ void unpack8(u32x4 g, f32x4& a, f32x4& b) { a = (f32x4){bf_lo(g.x), bf_hi(g.x), bf_lo(g.y), bf_hi(g.y)}; b = (f32x4){bf_lo(g.z), bf_hi(g.z), bf_lo(g.w), bf_hi(g.w)}; }
;     __device__ __forceinline__ void operator()(f32x4 (&acc)[2][2][4][2], const Unit& u, int wr, int wc, int fr, int fq) const {
;     ...
; #pragma unroll
;             for (int m = 0; m < 4; ++m)
; #pragma unroll
;                 for (int bj = 0; bj < 2; ++bj) { const int row = u.pm * 256 + ai * 128 + wr * 64 + m * 16 + fr, col = u.pn * 256 + bj * 128 + wc * 32 + 8 * fq;
;                     const f32x4 s0 = *(const f32x4*)(pscale + col), s1 = *(const f32x4*)(pscale + col + 4);
;                     f32x4 z0, z1; unpack8(zz[m][bj], z0, z1);
;                     *(u32x4*)(Y + (size_t)row * YW + EW + col) = pack8(acc[ai][bj][m][0] * s0 * z0, acc[ai][bj][m][1] * s1 * z1); }
;             asm volatile("" ::: "memory");
	v_pk_mul_f32 v[60:61], v[60:61], v[230:231]
	v_pk_mul_f32 v[62:63], v[62:63], v[224:225]
	v_pk_mul_f32 v[64:65], v[64:65], v[226:227]
	v_pk_mul_f32 v[62:63], v[62:63], v[110:111]
	v_pk_mul_f32 v[58:59], v[58:59], v[228:229]
	v_pk_mul_f32 v[64:65], v[64:65], v[94:95]
	v_pk_mul_f32 v[94:95], v[60:61], v[96:97]
	v_pk_mul_f32 v[60:61], v[58:59], v[112:113]
	v_cvt_pk_bf16_f32 v58, v62, v63
	v_mad_i64_i32 v[62:63], s[4:5], v101, s13, v[130:131]
	v_cvt_pk_bf16_f32 v59, v64, v65
	v_cvt_pk_bf16_f32 v60, v60, v61
	v_cvt_pk_bf16_f32 v61, v94, v95
	v_lshl_add_u64 v[94:95], v[62:63], 0, v[174:175]
	global_store_dwordx4 v[94:95], v[58:61], off offset:2048
	s_nop 1
	s_nop 0
	v_lshlrev_b32_e32 v96, 16, v90
	v_and_b32_e32 v97, 0xffff0000, v90
	v_lshlrev_b32_e32 v90, 16, v91
	v_and_b32_e32 v91, 0xffff0000, v91
	v_lshlrev_b32_e32 v102, 16, v92
	v_and_b32_e32 v103, 0xffff0000, v92
	v_lshlrev_b32_e32 v92, 16, v93
	v_and_b32_e32 v93, 0xffff0000, v93
	v_pk_mul_f32 v[52:53], v[52:53], v[238:239]
	v_pk_mul_f32 v[56:57], v[56:57], v[234:235]
	v_pk_mul_f32 v[54:55], v[54:55], v[232:233]
	v_pk_mul_f32 v[50:51], v[50:51], v[236:237]
	v_pk_mul_f32 v[56:57], v[56:57], v[90:91]
	v_pk_mul_f32 v[54:55], v[54:55], v[96:97]
	v_pk_mul_f32 v[58:59], v[52:53], v[92:93]
	v_pk_mul_f32 v[52:53], v[50:51], v[102:103]
	v_cvt_pk_bf16_f32 v50, v54, v55
	v_cvt_pk_bf16_f32 v51, v56, v57
	v_cvt_pk_bf16_f32 v52, v52, v53
	v_cvt_pk_bf16_f32 v53, v58, v59
	global_store_dwordx4 v[94:95], v[50:53], off offset:2304
	s_nop 1
	s_nop 0
	v_lshlrev_b32_e32 v58, 16, v86
	v_and_b32_e32 v59, 0xffff0000, v86
	v_lshlrev_b32_e32 v60, 16, v87
	v_and_b32_e32 v61, 0xffff0000, v87
	v_lshlrev_b32_e32 v62, 16, v88
	v_and_b32_e32 v63, 0xffff0000, v88
	v_lshlrev_b32_e32 v64, 16, v89
	v_and_b32_e32 v65, 0xffff0000, v89
	v_pk_mul_f32 v[44:45], v[44:45], v[230:231]
	v_pk_mul_f32 v[46:47], v[46:47], v[224:225]
	v_pk_mul_f32 v[48:49], v[48:49], v[226:227]
	v_pk_mul_f32 v[46:47], v[46:47], v[58:59]
	v_pk_mul_f32 v[42:43], v[42:43], v[228:229]
	v_pk_mul_f32 v[48:49], v[48:49], v[60:61]
	v_pk_mul_f32 v[50:51], v[44:45], v[64:65]
	v_pk_mul_f32 v[44:45], v[42:43], v[62:63]
	v_cvt_pk_bf16_f32 v42, v46, v47
	v_mad_i64_i32 v[46:47], s[4:5], v100, s13, v[130:131]
	v_cvt_pk_bf16_f32 v43, v48, v49
	v_cvt_pk_bf16_f32 v44, v44, v45
	v_cvt_pk_bf16_f32 v45, v50, v51
	v_lshl_add_u64 v[50:51], v[46:47], 0, v[174:175]
	global_store_dwordx4 v[50:51], v[42:45], off offset:2048
	s_nop 1
	s_nop 0
	v_lshlrev_b32_e32 v52, 16, v82
	v_and_b32_e32 v53, 0xffff0000, v82
	v_lshlrev_b32_e32 v54, 16, v83
	v_and_b32_e32 v55, 0xffff0000, v83
	v_lshlrev_b32_e32 v56, 16, v84
	v_and_b32_e32 v57, 0xffff0000, v84
	v_lshlrev_b32_e32 v58, 16, v85
	v_and_b32_e32 v59, 0xffff0000, v85
	v_pk_mul_f32 v[36:37], v[36:37], v[238:239]
	v_pk_mul_f32 v[40:41], v[40:41], v[234:235]
	v_pk_mul_f32 v[38:39], v[38:39], v[232:233]
	v_pk_mul_f32 v[34:35], v[34:35], v[236:237]
	v_pk_mul_f32 v[40:41], v[40:41], v[54:55]
	v_pk_mul_f32 v[38:39], v[38:39], v[52:53]
	v_pk_mul_f32 v[42:43], v[36:37], v[58:59]
	v_pk_mul_f32 v[36:37], v[34:35], v[56:57]
	v_cvt_pk_bf16_f32 v34, v38, v39
	v_cvt_pk_bf16_f32 v35, v40, v41
	v_cvt_pk_bf16_f32 v36, v36, v37
	v_cvt_pk_bf16_f32 v37, v42, v43
	global_store_dwordx4 v[50:51], v[34:37], off offset:2304
	s_nop 1
	s_nop 0
	v_lshlrev_b32_e32 v42, 16, v78
	v_and_b32_e32 v43, 0xffff0000, v78
	v_lshlrev_b32_e32 v44, 16, v79
	v_and_b32_e32 v45, 0xffff0000, v79
	v_lshlrev_b32_e32 v46, 16, v80
	v_and_b32_e32 v47, 0xffff0000, v80
	v_lshlrev_b32_e32 v48, 16, v81
	v_and_b32_e32 v49, 0xffff0000, v81
	v_pk_mul_f32 v[28:29], v[28:29], v[230:231]
	v_pk_mul_f32 v[30:31], v[30:31], v[224:225]
	v_pk_mul_f32 v[32:33], v[32:33], v[226:227]
	v_pk_mul_f32 v[30:31], v[30:31], v[42:43]
	v_pk_mul_f32 v[26:27], v[26:27], v[228:229]
	v_pk_mul_f32 v[32:33], v[32:33], v[44:45]
	v_pk_mul_f32 v[34:35], v[28:29], v[48:49]
	v_pk_mul_f32 v[28:29], v[26:27], v[46:47]
	v_cvt_pk_bf16_f32 v26, v30, v31
	v_mad_i64_i32 v[30:31], s[4:5], v99, s13, v[130:131]
	v_cvt_pk_bf16_f32 v27, v32, v33
	v_cvt_pk_bf16_f32 v28, v28, v29
	v_cvt_pk_bf16_f32 v29, v34, v35
	v_lshl_add_u64 v[34:35], v[30:31], 0, v[174:175]
	global_store_dwordx4 v[34:35], v[26:29], off offset:2048
	s_nop 1
	s_nop 0
	v_lshlrev_b32_e32 v36, 16, v70
	v_and_b32_e32 v37, 0xffff0000, v70
	v_lshlrev_b32_e32 v38, 16, v71
	v_and_b32_e32 v39, 0xffff0000, v71
	v_lshlrev_b32_e32 v40, 16, v72
	v_and_b32_e32 v41, 0xffff0000, v72
	v_lshlrev_b32_e32 v42, 16, v73
	v_and_b32_e32 v43, 0xffff0000, v73
	v_pk_mul_f32 v[20:21], v[20:21], v[238:239]
	v_pk_mul_f32 v[24:25], v[24:25], v[234:235]
	v_pk_mul_f32 v[22:23], v[22:23], v[232:233]
	v_pk_mul_f32 v[18:19], v[18:19], v[236:237]
	v_pk_mul_f32 v[24:25], v[24:25], v[38:39]
	v_pk_mul_f32 v[22:23], v[22:23], v[36:37]
	v_pk_mul_f32 v[26:27], v[20:21], v[42:43]
	v_pk_mul_f32 v[20:21], v[18:19], v[40:41]
	v_cvt_pk_bf16_f32 v18, v22, v23
	v_cvt_pk_bf16_f32 v19, v24, v25
	v_cvt_pk_bf16_f32 v20, v20, v21
	v_cvt_pk_bf16_f32 v21, v26, v27
	global_store_dwordx4 v[34:35], v[18:21], off offset:2304
	s_nop 1
	s_nop 0
	v_lshlrev_b32_e32 v26, 16, v74
	v_and_b32_e32 v27, 0xffff0000, v74
	v_lshlrev_b32_e32 v28, 16, v75
	v_and_b32_e32 v29, 0xffff0000, v75
	v_lshlrev_b32_e32 v30, 16, v76
	v_and_b32_e32 v31, 0xffff0000, v76
	v_lshlrev_b32_e32 v32, 16, v77
	v_and_b32_e32 v33, 0xffff0000, v77
	v_pk_mul_f32 v[12:13], v[12:13], v[230:231]
	v_pk_mul_f32 v[14:15], v[14:15], v[224:225]
	v_pk_mul_f32 v[16:17], v[16:17], v[226:227]
	v_pk_mul_f32 v[14:15], v[14:15], v[26:27]
	v_pk_mul_f32 v[10:11], v[10:11], v[228:229]
	v_pk_mul_f32 v[16:17], v[16:17], v[28:29]
	v_pk_mul_f32 v[18:19], v[12:13], v[32:33]
	v_pk_mul_f32 v[12:13], v[10:11], v[30:31]
	v_cvt_pk_bf16_f32 v10, v14, v15
	v_mad_i64_i32 v[14:15], s[4:5], v98, s13, v[130:131]
	v_cvt_pk_bf16_f32 v11, v16, v17
	v_cvt_pk_bf16_f32 v12, v12, v13
	v_cvt_pk_bf16_f32 v13, v18, v19
	v_lshl_add_u64 v[18:19], v[14:15], 0, v[174:175]
	global_store_dwordx4 v[18:19], v[10:13], off offset:2048
	s_nop 1
	s_nop 0
	v_lshlrev_b32_e32 v20, 16, v66
	v_and_b32_e32 v21, 0xffff0000, v66
	v_lshlrev_b32_e32 v22, 16, v67
	v_and_b32_e32 v23, 0xffff0000, v67
	v_lshlrev_b32_e32 v24, 16, v68
	v_and_b32_e32 v25, 0xffff0000, v68
	v_lshlrev_b32_e32 v26, 16, v69
	v_and_b32_e32 v27, 0xffff0000, v69
	s_mov_b64 s[4:5], -1
	v_pk_mul_f32 v[4:5], v[4:5], v[238:239]
	v_pk_mul_f32 v[8:9], v[8:9], v[234:235]
	v_pk_mul_f32 v[6:7], v[6:7], v[232:233]
	v_pk_mul_f32 v[2:3], v[2:3], v[236:237]
	v_pk_mul_f32 v[8:9], v[8:9], v[22:23]
	v_pk_mul_f32 v[6:7], v[6:7], v[20:21]
	v_pk_mul_f32 v[10:11], v[4:5], v[26:27]
	v_pk_mul_f32 v[4:5], v[2:3], v[24:25]
	v_cvt_pk_bf16_f32 v2, v6, v7
	v_cvt_pk_bf16_f32 v3, v8, v9
	v_cvt_pk_bf16_f32 v4, v4, v5
	v_cvt_pk_bf16_f32 v5, v10, v11
	global_store_dwordx4 v[18:19], v[2:5], off offset:2304
	s_nop 1
	s_cbranch_vccnz .LBB0_476
	s_andn2_b64 vcc, exec, s[40:41]
	s_cbranch_vccnz .LBB0_475
	s_barrier
	s_branch .LBB0_475
